# gates/merge/out tile loops enumerate only computed row tiles (last layer skips context rows): every workgroup gets the same tile count
# speedup vs baseline: 1.1466x; 1.0086x over previous
; DEV int bid_() { int b = blockIdx.x; asm volatile("" : "+s"(b)); return b; }
; __device__ void phase_gates(PRef p, int l, const bf16* H2, bf16* sA, bf16* sB) {
;   const int xcd_ = bid_() & 7, per_ = gridDim.x >> 3;
;   for (int t = bid_() >> 3; t < 36 * 12; t += per_) {
;     int rt = xcd_ + 8 * (t / 12), ct = t % 12;
;     if (skip_rt(l, rt)) continue;
;     f32x16 acc[2][2];
;     zero_acc<2>(acc);
;     gemm_tile<2>(acc, H2 + (size_t)rt * 128 * 1024, 1024, p.WT2 + (size_t)ct * 128 * 1024, 1024, 1024, sA, sB);
.LBB0_868:
	s_add_i32 s16, s16, s81
	s_movk_i32 s0, 0x1b0
	s_cmp_lg_u64 s[6:7], 0
	s_cselect_b32 s0, 0x180, s0
	s_cmp_lt_i32 s16, s0
	s_cbranch_scc0 .LBB0_876
.LBB0_869:
	s_mul_hi_i32 s0, s16, 0x2aaaaaab
	s_lshr_b32 s1, s0, 31
	s_ashr_i32 s0, s0, 1
	s_add_i32 s0, s0, s1
	s_mov_b32 s1, s0
	s_mov_b32 s12, -1
	s_mov_b32 s13, 15
	s_cmp_eq_u64 s[6:7], 0
	s_cbranch_scc1 .Lbalg_clr0
	s_lshr_b32 s10, s17, 1
	s_mov_b32 s12, 0xf7fbfdfe
	s_cmp_eq_u32 s10, 1
	s_cselect_b32 s12, 0xdfeff7fb, s12
	s_cmp_eq_u32 s10, 2
	s_cselect_b32 s12, 0x7fbfdfef, s12
	s_cmp_eq_u32 s10, 3
	s_cselect_b32 s12, 0xfeff7fbf, s12
	s_cselect_b32 s13, 13, 15
.Lbalg_clr0:
	s_cmp_eq_u32 s1, 0
	s_cbranch_scc1 .Lbalg_nth
.Lbalg_clr:
	s_add_u32 s10, s12, -1
	s_addc_u32 s11, s13, -1
	s_and_b64 s[12:13], s[12:13], s[10:11]
	s_sub_u32 s1, s1, 1
	s_cmp_lg_u32 s1, 0
	s_cbranch_scc1 .Lbalg_clr
.Lbalg_nth:
	s_ff1_i32_b64 s1, s[12:13]
	s_lshl_b32 s1, s1, 3
	s_or_b32 s10, s1, s17
	s_mul_i32 s0, s0, 12
	s_sub_i32 s12, s16, s0
	v_readlane_b32 s14, v245, 4
	v_readlane_b32 s15, v245, 5
	s_lshl_b32 s0, s10, 18
	s_add_u32 s98, s14, s0
	s_addc_u32 s99, s15, 0
	s_lshl_b32 s0, s12, 18
	s_waitcnt lgkmcnt(0)
	s_add_u32 s100, s4, s0
	s_addc_u32 s101, s5, 0
	v_and_b32_e32 v0, 63, v196
	v_lshrrev_b32_e32 v1, 6, v196
	v_lshrrev_b32_e32 v2, 3, v0
	v_readfirstlane_b32 s0, v1
	v_lshrrev_b32_e32 v78, 1, v2
	v_and_b32_e32 v79, 7, v0
	v_xor_b32_e32 v78, v79, v78
	v_lshlrev_b32_e32 v78, 4, v78
	v_lshl_or_b32 v68, v2, 11, v78
	v_xor_b32_e32 v69, 64, v68
	v_lshrrev_b32_e32 v78, 5, v0
	v_bfe_u32 v79, v0, 1, 3
	v_and_b32_e32 v2, 31, v0
	v_lshrrev_b32_e32 v0, 1, v1
	v_and_b32_e32 v1, 1, v1
	v_lshl_add_u32 v0, v0, 6, v2
	v_lshl_add_u32 v1, v1, 6, v2
	v_lshlrev_b32_e32 v0, 7, v0
	v_lshlrev_b32_e32 v1, 7, v1
	v_add_u32_e32 v1, 0x4000, v1
	v_add_u32_e32 v2, 0, v78
	v_xor_b32_e32 v2, v2, v79
	v_lshl_add_u32 v70, v2, 4, v0
	v_lshl_add_u32 v74, v2, 4, v1
	v_add_u32_e32 v2, 2, v78
	v_xor_b32_e32 v2, v2, v79
	v_lshl_add_u32 v71, v2, 4, v0
	v_lshl_add_u32 v75, v2, 4, v1
	v_add_u32_e32 v2, 4, v78
	v_xor_b32_e32 v2, v2, v79
	v_lshl_add_u32 v72, v2, 4, v0
	v_lshl_add_u32 v76, v2, 4, v1
	v_add_u32_e32 v2, 6, v78
	v_xor_b32_e32 v2, v2, v79
	v_lshl_add_u32 v73, v2, 4, v0
	v_lshl_add_u32 v77, v2, 4, v1
	s_lshl_b32 s1, s0, 16
	s_lshl_b32 s0, s0, 12
	s_add_u32 s98, s98, s1
	s_addc_u32 s99, s99, 0
	s_add_u32 s100, s100, s1
	s_addc_u32 s101, s101, 0
	s_waitcnt lgkmcnt(0)
	s_barrier
	s_add_u32 m0, s0, 0x0
	s_nop 0
	global_load_lds_dwordx4 v68, s[98:99]
	s_add_u32 m0, s0, 0x400
	s_add_u32 s14, s98, 0x4000
	s_addc_u32 s15, s99, 0
	global_load_lds_dwordx4 v69, s[14:15]
	s_add_u32 m0, s0, 0x800
	s_add_u32 s14, s98, 0x8000
	s_addc_u32 s15, s99, 0
	global_load_lds_dwordx4 v68, s[14:15]
	s_add_u32 m0, s0, 0xc00
	s_add_u32 s14, s98, 0xc000
	s_addc_u32 s15, s99, 0
	global_load_lds_dwordx4 v69, s[14:15]
	s_add_u32 m0, s0, 0x4000
	s_nop 0
	global_load_lds_dwordx4 v68, s[100:101]
	s_add_u32 m0, s0, 0x4400
	s_add_u32 s14, s100, 0x4000
	s_addc_u32 s15, s101, 0
	global_load_lds_dwordx4 v69, s[14:15]
	s_add_u32 m0, s0, 0x4800
	s_add_u32 s14, s100, 0x8000
	s_addc_u32 s15, s101, 0
	global_load_lds_dwordx4 v68, s[14:15]
	s_add_u32 m0, s0, 0x4c00
	s_add_u32 s14, s100, 0xc000
	s_addc_u32 s15, s101, 0
	global_load_lds_dwordx4 v69, s[14:15]
	s_add_u32 s98, s98, 0x80
	s_addc_u32 s99, s99, 0
	s_add_u32 s100, s100, 0x80
	s_addc_u32 s101, s101, 0
	v_mov_b32_e32 v4, 0
	v_mov_b32_e32 v5, 0
	v_mov_b32_e32 v6, 0
	v_mov_b32_e32 v7, 0
	v_mov_b32_e32 v8, 0
	v_mov_b32_e32 v9, 0
	v_mov_b32_e32 v10, 0
	v_mov_b32_e32 v11, 0
	v_mov_b32_e32 v12, 0
	v_mov_b32_e32 v13, 0
	v_mov_b32_e32 v14, 0
	v_mov_b32_e32 v15, 0
	v_mov_b32_e32 v16, 0
	v_mov_b32_e32 v17, 0
	v_mov_b32_e32 v18, 0
	v_mov_b32_e32 v19, 0
	v_mov_b32_e32 v20, 0
	v_mov_b32_e32 v21, 0
	v_mov_b32_e32 v22, 0
	v_mov_b32_e32 v23, 0
	v_mov_b32_e32 v24, 0
	v_mov_b32_e32 v25, 0
	v_mov_b32_e32 v26, 0
	v_mov_b32_e32 v27, 0
	v_mov_b32_e32 v28, 0
	v_mov_b32_e32 v29, 0
	v_mov_b32_e32 v30, 0
	v_mov_b32_e32 v31, 0
	v_mov_b32_e32 v32, 0
	v_mov_b32_e32 v33, 0
	v_mov_b32_e32 v34, 0
	v_mov_b32_e32 v35, 0
	v_mov_b32_e32 v36, 0
	v_mov_b32_e32 v37, 0
	v_mov_b32_e32 v38, 0
	v_mov_b32_e32 v39, 0
	v_mov_b32_e32 v40, 0
	v_mov_b32_e32 v41, 0
	v_mov_b32_e32 v42, 0
	v_mov_b32_e32 v43, 0
	v_mov_b32_e32 v44, 0
	v_mov_b32_e32 v45, 0
	v_mov_b32_e32 v46, 0
	v_mov_b32_e32 v47, 0
	v_mov_b32_e32 v48, 0
	v_mov_b32_e32 v49, 0
	v_mov_b32_e32 v50, 0
	v_mov_b32_e32 v51, 0
	v_mov_b32_e32 v52, 0
	v_mov_b32_e32 v53, 0
	v_mov_b32_e32 v54, 0
	v_mov_b32_e32 v55, 0
	v_mov_b32_e32 v56, 0
	v_mov_b32_e32 v57, 0
	v_mov_b32_e32 v58, 0
	v_mov_b32_e32 v59, 0
	v_mov_b32_e32 v60, 0
	v_mov_b32_e32 v61, 0
	v_mov_b32_e32 v62, 0
	v_mov_b32_e32 v63, 0
	v_mov_b32_e32 v64, 0
	v_mov_b32_e32 v65, 0
	v_mov_b32_e32 v66, 0
	v_mov_b32_e32 v67, 0
	s_mov_b32 s11, 0

; DEV int bid_() { int b = blockIdx.x; asm volatile("" : "+s"(b)); return b; }
; __device__ void phase_merge(PRef p, int l, const bf16* H2, bf16* M, bf16* sA, bf16* sB) {
;   const int xcd_ = bid_() & 7, per_ = gridDim.x >> 3;
;   for (int t = bid_() >> 3; t < 36 * 8; t += per_) {
;     int rt = xcd_ + 8 * (t / 8), ct = t % 8;
;     if (skip_rt(l, rt)) continue;
.LBB0_952:
	s_add_i32 s58, s58, s81
	s_movk_i32 s0, 0x120
	s_cmp_lg_u64 s[6:7], 0
	s_cselect_b32 s0, 0x100, s0
	s_cmp_lt_i32 s58, s0
	s_cbranch_scc0 .LBB0_1003
.LBB0_953:
	s_lshr_b32 s0, s58, 3
	s_mov_b32 s14, -1
	s_mov_b32 s15, 15
	s_cmp_eq_u64 s[6:7], 0
	s_cbranch_scc1 .Lbalm_clr0
	s_lshr_b32 s20, s62, 1
	s_mov_b32 s14, 0xf7fbfdfe
	s_cmp_eq_u32 s20, 1
	s_cselect_b32 s14, 0xdfeff7fb, s14
	s_cmp_eq_u32 s20, 2
	s_cselect_b32 s14, 0x7fbfdfef, s14
	s_cmp_eq_u32 s20, 3
	s_cselect_b32 s14, 0xfeff7fbf, s14
	s_cselect_b32 s15, 13, 15
.Lbalm_clr0:
	s_cmp_eq_u32 s0, 0
	s_cbranch_scc1 .Lbalm_nth
.Lbalm_clr:
	s_add_u32 s20, s14, -1
	s_addc_u32 s21, s15, -1
	s_and_b64 s[14:15], s[14:15], s[20:21]
	s_sub_u32 s0, s0, 1
	s_cmp_lg_u32 s0, 0
	s_cbranch_scc1 .Lbalm_clr
.Lbalm_nth:
	s_ff1_i32_b64 s0, s[14:15]
	s_lshl_b32 s0, s0, 3
	s_or_b32 s18, s0, s62
	s_mov_b32 s0, s58
	s_ashr_i32 s0, s0, 3
	s_lshl_b32 s28, s0, 3
	s_ashr_i32 s19, s18, 31
	s_sub_i32 s20, s58, s28
	s_lshl_b64 s[14:15], s[18:19], 7
	s_lshl_b64 s[0:1], s[18:19], 18
	v_readlane_b32 s16, v245, 4
	v_readlane_b32 s17, v245, 5
	s_add_u32 s16, s16, s0
	s_addc_u32 s17, s17, s1
	s_lshl_b32 s20, s20, 7
	s_ashr_i32 s21, s20, 31
	s_lshl_b32 s94, s18, 7
	s_lshl_b64 s[0:1], s[20:21], 1
	s_add_u32 s22, s70, s0
	s_addc_u32 s23, s71, s1
	s_lshl_b64 s[0:1], s[20:21], 11
	v_readlane_b32 s18, v245, 24
	s_add_u32 s24, s18, s0
	v_readlane_b32 s18, v245, 2
	s_addc_u32 s25, s18, s1
	v_readlane_b32 s18, v245, 14
	s_add_u32 s26, s18, s0
	v_readlane_b32 s18, v245, 12
	s_addc_u32 s27, s18, s1
	v_readlane_b32 s18, v245, 18
	s_add_u32 s36, s18, s0
	v_readlane_b32 s18, v245, 20
	s_addc_u32 s37, s18, s1
	v_readlane_b32 s18, v245, 22
	s_add_u32 s38, s18, s0
	v_readlane_b32 s18, v245, 26
	s_addc_u32 s39, s18, s1
	v_readlane_b32 s18, v245, 32
	s_add_u32 s40, s18, s0
	v_readlane_b32 s18, v245, 33
	s_addc_u32 s41, s18, s1
	v_readlane_b32 s18, v245, 34
	s_add_u32 s42, s18, s0
	v_readlane_b32 s0, v245, 35
	s_addc_u32 s43, s0, s1
	s_lshl_b64 s[0:1], s[20:21], 10
	v_readlane_b32 s18, v245, 36
	s_add_u32 s44, s18, s0
	v_readlane_b32 s18, v245, 37
	s_addc_u32 s45, s18, s1
	v_readlane_b32 s18, v245, 38
	s_add_u32 s46, s18, s0
	v_readlane_b32 s18, v245, 39
	s_addc_u32 s47, s18, s1
	v_readlane_b32 s18, v245, 40
	s_add_u32 s48, s18, s0
	v_readlane_b32 s18, v245, 41
	s_addc_u32 s49, s18, s1
	v_readlane_b32 s18, v245, 42
	s_add_u32 s50, s18, s0
	v_readlane_b32 s18, v245, 43
	s_addc_u32 s51, s18, s1
	v_readlane_b32 s18, v245, 44
	s_add_u32 s78, s18, s0
	v_readlane_b32 s18, v245, 45
	s_addc_u32 s79, s18, s1
	v_readlane_b32 s18, v245, 46
	s_add_u32 s80, s18, s0
	s_addc_u32 s81, s63, s1
	s_add_u32 s86, s90, s0
	s_addc_u32 s87, s91, s1
	s_or_b32 s0, s62, s28
	s_ashr_i32 s1, s0, 31
	s_lshl_b64 s[88:89], s[0:1], 8
	s_or_b32 s96, s88, 0xc0
	s_mov_b32 s97, s89
	s_or_b32 s18, s88, 0x80
	s_mov_b32 s19, s89
	s_or_b32 s88, s88, 64
	s_mov_b32 s95, 0
	s_branch .LBB0_957

; DEV int bid_() { int b = blockIdx.x; asm volatile("" : "+s"(b)); return b; }
; __device__ void phase_out(PRef p, int l, const bf16* M, const float* xl, const float* xc, bf16* sA, bf16* sB) {
;   const int xcd_ = bid_() & 7, per_ = gridDim.x >> 3;
;   for (int t = bid_() >> 3; t < 36 * 8; t += per_) {
;     int rt = xcd_ + 8 * (t / 8), ct = t % 8;
;     if (skip_rt(l, rt)) continue;
;     f32x16 acc[2][2];
;     zero_acc<2>(acc);
;     gemm_tile<2>(acc, M + (size_t)rt * 128 * 1024, 1024, p.WOUT + (size_t)ct * 128 * 1024, 1024, 1024, sA, sB);
;     int b = rt / 18;
;     bool isctx = (rt % 18) < 2;
;     const float* gate = p.MOD + ((size_t)l * 17 + (isctx ? 16 : b)) * 3072 + 2048;
.LBB0_1081:
	s_add_i32 s28, s28, s81
	s_movk_i32 s4, 0x120
	s_cmp_lg_u64 s[6:7], 0
	s_cselect_b32 s4, 0x100, s4
	s_cmp_lt_i32 s28, s4
	s_cbranch_scc0 .LBB0_1112
.LBB0_1082:
	s_lshr_b32 s5, s28, 3
	s_mov_b32 s14, -1
	s_mov_b32 s15, 15
	s_cmp_eq_u64 s[6:7], 0
	s_cbranch_scc1 .Lbalo_clr0
	s_lshr_b32 s22, s34, 1
	s_mov_b32 s14, 0xf7fbfdfe
	s_cmp_eq_u32 s22, 1
	s_cselect_b32 s14, 0xdfeff7fb, s14
	s_cmp_eq_u32 s22, 2
	s_cselect_b32 s14, 0x7fbfdfef, s14
	s_cmp_eq_u32 s22, 3
	s_cselect_b32 s14, 0xfeff7fbf, s14
	s_cselect_b32 s15, 13, 15
.Lbalo_clr0:
	s_cmp_eq_u32 s5, 0
	s_cbranch_scc1 .Lbalo_nth
.Lbalo_clr:
	s_add_u32 s22, s14, -1
	s_addc_u32 s23, s15, -1
	s_and_b64 s[14:15], s[14:15], s[22:23]
	s_sub_u32 s5, s5, 1
	s_cmp_lg_u32 s5, 0
	s_cbranch_scc1 .Lbalo_clr
.Lbalo_nth:
	s_ff1_i32_b64 s5, s[14:15]
	s_lshl_b32 s4, s5, 3
	s_or_b32 s4, s4, s34
	s_mov_b32 s5, s28
	s_mul_hi_i32 s14, s4, 0x38e38e39
	s_lshr_b32 s15, s14, 31
	s_ashr_i32 s14, s14, 2
	s_add_i32 s18, s14, s15
	s_mul_i32 s14, s18, 18
	s_sub_i32 s14, s4, s14
	s_cmp_lt_i32 s14, 2
	s_cselect_b64 s[22:23], -1, 0
	s_cmp_gt_i32 s14, 1
	s_cselect_b64 s[24:25], -1, 0
	s_ashr_i32 s5, s5, 3
	s_lshl_b32 s5, s5, 3
	s_sub_i32 s20, s28, s5
	s_lshl_b32 s14, s4, 18
	s_add_u32 s98, s70, s14
	s_addc_u32 s99, s71, 0
	s_lshl_b32 s14, s20, 18
	s_waitcnt lgkmcnt(0)
	s_add_u32 s100, s12, s14
	s_addc_u32 s101, s13, 0
	s_lshl_b32 s36, s4, 7
	s_mul_i32 s14, s18, 0x900
	s_sub_u32 s14, s36, s14
	s_andn2_b64 vcc, exec, s[24:25]
	s_cbranch_vccnz .Lout_ctx
	s_sub_u32 s14, s14, 0x100
	s_lshl_b32 s15, s18, 11
	s_mov_b64 s[30:31], s[40:41]
	s_mov_b64 s[26:27], s[10:11]
	s_branch .Lout_ptr
